# v31 + attention: next pass K(0) LDS-DMA and Q-fragment loads hoisted into the last tail step of the current pass (right after the last QK MFMA), hiding the per-pass cold-start latency
# baseline (speedup 1.0000x reference)
; __device__ __forceinline__ float wave_sum(float v) {
; #pragma unroll
;     for (int o = 1; o < 64; o <<= 1) v += __shfl_xor(v, o);
;     return v;
; __global__ void __launch_bounds__(512, 2) fwd_kernel(Args args) {
;     ...
;         const float s1 = wave_sum(lam_q1[lane] * lam_k1[lane]), s2 = wave_sum(lam_q2[lane] * lam_k2[lane]);
;         const float lam = __expf(s1) - __expf(s2) + LAMBDA_INIT;
;         for (int i = 0; ; ++i) { const int L = i * G + vcu, NU = NBATCH * NH * (SEQ / 256); if (L >= NU) break;
;             const int bh = L >> 3, qb = L & 7, Ln = L + G, nbh = Ln >> 3;
;             att::attn_unit(bh >> 3, bh & 7, qb, i == 0, Ln < NU, nbh >> 3, nbh & 7, QO, KB, VB, lam, (char*)lds_raw); }
.LBB0_367:
	s_or_b64 exec, exec, s[0:1]
	v_lshlrev_b32_e32 v1, 2, v162
	s_barrier
	global_load_dword v2, v1, s[48:49]
	global_load_dword v3, v1, s[50:51]
	global_load_dword v4, v1, s[16:17]
	global_load_dword v5, v1, s[18:19]
	v_mbcnt_lo_u32_b32 v1, -1, 0
	v_mbcnt_hi_u32_b32 v6, -1, v1
	v_and_b32_e32 v1, 64, v6
	v_xor_b32_e32 v7, 1, v6
	v_add_u32_e32 v13, 64, v1
	v_cmp_lt_i32_e32 vcc, v7, v13
	v_xor_b32_e32 v8, 2, v6
	v_xor_b32_e32 v9, 4, v6
	v_cndmask_b32_e32 v1, v6, v7, vcc
	v_lshlrev_b32_e32 v1, 2, v1
	v_cmp_lt_i32_e32 vcc, v8, v13
	v_xor_b32_e32 v10, 8, v6
	v_xor_b32_e32 v11, 16, v6
	v_cndmask_b32_e32 v8, v6, v8, vcc
	v_lshlrev_b32_e32 v234, 2, v8
	v_cmp_lt_i32_e32 vcc, v9, v13
	v_xor_b32_e32 v12, 32, v6
	s_cmpk_gt_i32 s86, 0x5ff
	s_mov_b32 s1, 0
	s_waitcnt vmcnt(2)
	v_mul_f32_e32 v7, v2, v3
	ds_bpermute_b32 v7, v1, v7
	s_waitcnt vmcnt(0)
	v_mul_f32_e32 v14, v4, v5
	ds_bpermute_b32 v14, v1, v14
	s_waitcnt lgkmcnt(1)
	v_fmac_f32_e32 v7, v2, v3
	ds_bpermute_b32 v2, v234, v7
	s_waitcnt lgkmcnt(1)
	v_fmac_f32_e32 v14, v4, v5
	ds_bpermute_b32 v3, v234, v14
	v_cndmask_b32_e32 v4, v6, v9, vcc
	v_lshlrev_b32_e32 v235, 2, v4
	s_waitcnt lgkmcnt(1)
	v_add_f32_e32 v2, v7, v2
	ds_bpermute_b32 v4, v235, v2
	s_waitcnt lgkmcnt(1)
	v_add_f32_e32 v3, v14, v3
	ds_bpermute_b32 v5, v235, v3
	v_cmp_lt_i32_e32 vcc, v10, v13
	s_waitcnt lgkmcnt(1)
	v_add_f32_e32 v2, v2, v4
	v_cndmask_b32_e32 v7, v6, v10, vcc
	v_lshlrev_b32_e32 v236, 2, v7
	s_waitcnt lgkmcnt(0)
	v_add_f32_e32 v3, v3, v5
	ds_bpermute_b32 v4, v236, v2
	ds_bpermute_b32 v5, v236, v3
	v_cmp_lt_i32_e32 vcc, v11, v13
	s_waitcnt lgkmcnt(1)
	v_add_f32_e32 v2, v2, v4
	v_cndmask_b32_e32 v7, v6, v11, vcc
	v_lshlrev_b32_e32 v237, 2, v7
	s_waitcnt lgkmcnt(0)
	v_add_f32_e32 v3, v3, v5
	ds_bpermute_b32 v4, v237, v2
	ds_bpermute_b32 v5, v237, v3
	v_cmp_lt_i32_e32 vcc, v12, v13
	s_waitcnt lgkmcnt(1)
	v_add_f32_e32 v2, v2, v4
	v_cndmask_b32_e32 v6, v6, v12, vcc
	v_lshlrev_b32_e32 v6, 2, v6
	s_waitcnt lgkmcnt(0)
	v_add_f32_e32 v3, v3, v5
	ds_bpermute_b32 v4, v6, v2
	ds_bpermute_b32 v5, v6, v3
	s_cbranch_scc1 .LBB0_385
	s_waitcnt lgkmcnt(1)
	v_add_f32_e32 v2, v2, v4
	s_waitcnt lgkmcnt(0)
	v_add_f32_e32 v3, v3, v5
	v_mul_f32_e32 v2, 0x3fb8aa3b, v2
	v_mul_f32_e32 v3, 0x3fb8aa3b, v3
	v_exp_f32_e32 v2, v2
	v_exp_f32_e32 v3, v3
	s_add_u32 s56, s62, 0xd220000
	s_addc_u32 s57, s63, 0
	s_lshl_b32 s72, s86, 8
	s_lshl_b32 s73, s15, 8
	v_writelane_b32 v248, s78, 4
	v_sub_f32_e32 v2, v2, v3
	s_add_u32 s76, s62, 0x13220000
	s_mov_b32 s65, s80
	v_writelane_b32 v248, s79, 5
	v_add_f32_e32 v238, 0x3e4ccccd, v2
	s_addc_u32 s77, s63, 0
	s_movk_i32 s78, 0x1e0
	s_mov_b64 s[2:3], 0x800
	s_mov_b64 s[4:5], 0x20000
	s_mov_b64 s[8:9], 0x20800
	s_mov_b64 s[10:11], 0x3c0000
	s_mov_b64 s[16:17], 0x3c0800
	s_mov_b64 s[18:19], 0x3e0000
	s_mov_b64 s[20:21], 0x3e0800
	v_mov_b32_e32 v203, 0
	s_mov_b64 s[22:23], 0x40000
	s_mov_b64 s[24:25], 0x60000
	s_mov_b64 s[30:31], 0x80000
	s_mov_b64 s[44:45], 0x40800
	v_mov_b32_e32 v239, 0x358637bd
	s_movk_i32 s79, 0xffe0
	s_mov_b32 s0, s86
	s_mov_b32 s80, 0
	v_readfirstlane_b32 s98, v0
	s_lshr_b32 s98, s98, 6
	s_cmp_ge_u32 s98, 4
	s_cselect_b32 s98, 1, 0
	s_mov_b32 s101, 0
	s_branch .LBB0_370

; #define DMA_K(t, slot) glds16(ksrc + (long)(t) * KVBLK * DM, (unsigned)__builtin_amdgcn_readfirstlane(kdst + (slot) * KSLOT))
; #define DMA_V(t, slot) do { glds16(vsrc0 + (long)(t) * KVBLK * DM, (unsigned)__builtin_amdgcn_readfirstlane(vdst + (slot) * VSLOT)); \
;         glds16(vsrc0 + (long)(t) * KVBLK * DM + 1024, (unsigned)__builtin_amdgcn_readfirstlane(vdst + (slot) * VSLOT + 8192)); } while (0)
; __device__ __forceinline__ void attn_unit(int b, int h, int qb, bool first, bool has_next, int nb, int nh, bf16_t* QO, const bf16_t* __restrict__ K, const bf16_t* __restrict__ V, float lam, char* shm) {
;     ...
;         const bf16_t* ksrc = K + rowbase * DM + hm * 1024 + klane;
;         const bf16_t* Qw = QO + (rowbase + q0 + wid * 32) * DM + hm * 1024;
;         bf16x8 qr[4];
; #pragma unroll
;         for (int d0 = 0; d0 < 4; ++d0) qr[d0] = *reinterpret_cast<const bf16x8*>(&Qw[(long)((r32 >> 4) * 32 + (d0 >> 1)) * 512 + (r32 & 15) * 32 + (d0 & 1) * 16 + hi * 8]);
;     ...
;         if (map == 0 && first) { DMA_K(0, 0); DMA_V(0, 0); DMA_K(1, 1); DMA_K(2, 2); }
.LBB0_372:
	s_or_b32 s0, s7, s89
	s_lshl_b64 s[52:53], s[0:1], 1
	v_lshl_add_u64 v[2:3], v[226:227], 0, s[52:53]
	s_cmp_lg_u32 s101, 0
	s_mov_b32 s101, 0
	s_cbranch_scc1 .Lqh_skip
	global_load_dwordx4 v[190:193], v[2:3], off
	global_load_dwordx4 v[186:189], v[2:3], off offset:32
	global_load_dwordx4 v[182:185], v[2:3], off offset:1024
	global_load_dwordx4 v[178:181], v[2:3], off offset:1056
.Lqh_skip:
	s_and_b64 s[60:61], s[46:47], s[54:55]
	s_andn2_b64 vcc, exec, s[60:61]
	v_lshl_add_u64 v[232:233], v[206:207], 0, s[52:53]
	s_cbranch_vccnz .LBB0_374
	s_mov_b32 s0, m0
	s_mov_b32 m0, s91
	s_nop 0
	global_load_lds_dwordx4 v[232:233], off
	s_mov_b32 m0, s0
	s_cmp_lg_u32 0, -1
	s_mov_b32 s0, m0
	s_mov_b32 m0, s92
	s_nop 0
	global_load_lds_dwordx4 v[204:205], off
	s_mov_b32 m0, s0
	s_cselect_b32 s0, 0, 0
	s_add_i32 s0, s0, s90
	s_add_i32 s6, s0, 0x8000
	s_mov_b32 s12, m0
	s_mov_b32 m0, s6
	s_nop 0
	global_load_lds_dwordx4 v[208:209], off
	s_mov_b32 m0, s12
	v_lshl_add_u64 v[2:3], v[232:233], 0, s[4:5]
	s_add_i32 s6, s0, 0x2000
	s_mov_b32 s12, m0
	s_mov_b32 m0, s6
	s_nop 0
	global_load_lds_dwordx4 v[2:3], off
	s_mov_b32 m0, s12
	v_lshl_add_u64 v[2:3], v[232:233], 0, s[22:23]
	s_addk_i32 s0, 0x4000
	s_mov_b32 s6, m0
	s_mov_b32 m0, s0
	s_nop 0
	global_load_lds_dwordx4 v[2:3], off
	s_mov_b32 m0, s6

; #define ATT_WAIT_BAR(N) asm volatile("s_waitcnt vmcnt(" #N ") lgkmcnt(0)\n\ts_barrier" ::: "memory")
; #define ROT() do { sl_prev = sl_cur; sl_cur = sl_next; sl_next = (sl_next == 2) ? 0 : sl_next + 1; } while (0)
; __device__ __forceinline__ void attn_unit(int b, int h, int qb, bool first, bool has_next, int nb, int nh, bf16_t* QO, const bf16_t* __restrict__ K, const bf16_t* __restrict__ V, float lam, char* shm) {
;     ...
;         int t = 1;
; #pragma unroll 1
;         for (; t + 1 <= NT - 4; t += 2) {
;             STEP(pB0, pB1, pA0, pA1, t, true, true, true);     ATT_WAIT_BAR(3); ROT();
;             STEP(pA0, pA1, pB0, pB1, t + 1, true, true, true); ATT_WAIT_BAR(3); ROT();
;         }
;         STEP(pB0, pB1, pA0, pA1, NT - 3, false, true, true);   ATT_WAIT_BAR(2); ROT();
.Lst_b1:
	s_cmp_lg_u32 s33, 2
	s_mov_b32 s60, s0
	s_cselect_b32 s0, s12, 0
	s_add_i32 s6, s6, 2
	v_lshl_add_u64 v[146:147], v[146:147], 0, s[22:23]
	v_mov_b64_e32 v[148:149], v[106:107]
	s_mov_b32 s7, s33
	s_cmp_lt_u32 s6, 26
	s_cbranch_scc1 .LBB0_375
	ds_read_b64_tr_b16 v[106:107], v241 offset:40960
	ds_read_b64_tr_b16 v[108:109], v241 offset:41472
	v_add_f32_e32 v110, v82, v83
	v_add_f32_e32 v110, v84, v110
	v_add_f32_e32 v110, v85, v110
	v_add_f32_e32 v110, v86, v110
	v_add_f32_e32 v110, v87, v110
	v_cvt_pk_bf16_f32 v174, v82, v83
	v_cvt_pk_bf16_f32 v175, v84, v85
	v_mfma_f32_32x32x16_bf16 v[146:161], v[102:105], v[190:193], 0
	ds_read_b64_tr_b16 v[82:83], v241 offset:45056
	ds_read_b64_tr_b16 v[84:85], v241 offset:45568
	v_mfma_f32_32x32x16_bf16 v[114:129], v[98:101], v[190:193], 0
	v_add_f32_e32 v102, v88, v110
	v_add_f32_e32 v102, v89, v102
	v_add_f32_e32 v102, v90, v102
	v_add_f32_e32 v102, v91, v102
	v_cvt_pk_bf16_f32 v176, v86, v87
	v_cvt_pk_bf16_f32 v177, v88, v89
	ds_read_b64_tr_b16 v[86:87], v241 offset:49152
	ds_read_b64_tr_b16 v[88:89], v241 offset:49664
	v_add_f32_e32 v98, v92, v102
	v_add_f32_e32 v98, v93, v98
	v_add_f32_e32 v98, v94, v98
	v_add_f32_e32 v98, v95, v98
	v_cvt_pk_bf16_f32 v170, v90, v91
	v_cvt_pk_bf16_f32 v171, v92, v93
	v_mfma_f32_32x32x16_bf16 v[146:161], v[198:201], v[186:189], v[146:161]
	ds_read_b64_tr_b16 v[90:91], v241 offset:53248
	ds_read_b64_tr_b16 v[92:93], v241 offset:53760
	v_mfma_f32_32x32x16_bf16 v[114:129], v[142:145], v[186:189], v[114:129]
	v_add_f32_e32 v98, v96, v98
	v_add_f32_e32 v98, v97, v98
	v_add_f32_e32 v98, v66, v98
	v_add_f32_e32 v98, v67, v98
	v_cvt_pk_bf16_f32 v172, v94, v95
	v_cvt_pk_bf16_f32 v173, v96, v97
	s_nop 0
	v_add_f32_e32 v94, v68, v98
	v_add_f32_e32 v94, v69, v94
	v_add_f32_e32 v94, v70, v94
	v_add_f32_e32 v94, v71, v94
	v_cvt_pk_bf16_f32 v166, v66, v67
	v_cvt_pk_bf16_f32 v167, v68, v69
	v_mfma_f32_32x32x16_bf16 v[146:161], v[194:197], v[182:185], v[146:161]
	v_mfma_f32_32x32x16_bf16 v[114:129], v[134:137], v[182:185], v[114:129]
	v_add_f32_e32 v66, v72, v94
	v_add_f32_e32 v66, v73, v66
	v_add_f32_e32 v66, v74, v66
	v_add_f32_e32 v66, v75, v66
	v_cvt_pk_bf16_f32 v168, v70, v71
	v_cvt_pk_bf16_f32 v169, v72, v73
	s_nop 0
	v_add_f32_e32 v66, v76, v66
	v_add_f32_e32 v66, v77, v66
	v_add_f32_e32 v66, v78, v66
	v_add_f32_e32 v66, v79, v66
	v_cvt_pk_bf16_f32 v162, v74, v75
	v_cvt_pk_bf16_f32 v163, v76, v77
	s_waitcnt lgkmcnt(9)
	v_mfma_f32_32x32x16_bf16 v[146:161], v[138:141], v[178:181], v[146:161]
	s_waitcnt lgkmcnt(8)
	v_mfma_f32_32x32x16_bf16 v[114:129], v[130:133], v[178:181], v[114:129]
	v_add_f32_e32 v66, v80, v66
	v_add_f32_e32 v66, v81, v66
	v_add_f32_e32 v194, 0, v66
	v_cvt_pk_bf16_f32 v164, v78, v79
	v_cvt_pk_bf16_f32 v165, v80, v81
	s_mov_b32 s0, m0
	s_mov_b32 m0, s92
	s_nop 0
	global_load_lds_dwordx4 v[214:215], off
	s_mov_b32 m0, s0
	s_add_i32 s0, s92, 0x2000
	s_mov_b32 s6, m0
	s_mov_b32 m0, s0
	s_nop 0
	global_load_lds_dwordx4 v[216:217], off
	s_mov_b32 m0, s6
	s_waitcnt lgkmcnt(6)
	v_mfma_f32_32x32x16_bf16 v[50:65], v[174:177], v[106:109], v[50:65]
	s_nop 1
	v_exp_f32_e32 v146, v146
	v_exp_f32_e32 v147, v147
	ds_read_b64_tr_b16 v[66:67], v241 offset:41984
	ds_read_b64_tr_b16 v[68:69], v241 offset:42496
	s_waitcnt lgkmcnt(6)
	v_mfma_f32_32x32x16_bf16 v[34:49], v[174:177], v[82:85], v[34:49]
	v_exp_f32_e32 v148, v148
	v_exp_f32_e32 v149, v149
	ds_read_b64_tr_b16 v[70:71], v241 offset:46080
	ds_read_b64_tr_b16 v[72:73], v241 offset:46592
	s_waitcnt lgkmcnt(6)
	v_mfma_f32_32x32x16_bf16 v[18:33], v[174:177], v[86:89], v[18:33]
	v_exp_f32_e32 v150, v150
	v_exp_f32_e32 v151, v151
	ds_read_b64_tr_b16 v[74:75], v241 offset:50176
	ds_read_b64_tr_b16 v[76:77], v241 offset:50688
	s_waitcnt lgkmcnt(6)
	v_mfma_f32_32x32x16_bf16 v[2:17], v[174:177], v[90:93], v[2:17]
	v_exp_f32_e32 v152, v152
	v_exp_f32_e32 v153, v153
	ds_read_b64_tr_b16 v[78:79], v241 offset:54272
	ds_read_b64_tr_b16 v[80:81], v241 offset:54784
	s_waitcnt lgkmcnt(6)
	v_mfma_f32_32x32x16_bf16 v[50:65], v[170:173], v[66:69], v[50:65]
	v_exp_f32_e32 v154, v154
	v_exp_f32_e32 v155, v155
	ds_read_b64_tr_b16 v[82:83], v241 offset:43008
	ds_read_b64_tr_b16 v[84:85], v241 offset:43520
	s_waitcnt lgkmcnt(6)
	v_mfma_f32_32x32x16_bf16 v[34:49], v[170:173], v[70:73], v[34:49]
	v_exp_f32_e32 v156, v156
	v_exp_f32_e32 v157, v157
	ds_read_b64_tr_b16 v[66:67], v241 offset:47104
	ds_read_b64_tr_b16 v[68:69], v241 offset:47616
	s_waitcnt lgkmcnt(6)
	v_mfma_f32_32x32x16_bf16 v[18:33], v[170:173], v[74:77], v[18:33]
	v_exp_f32_e32 v158, v158
	v_exp_f32_e32 v159, v159
	ds_read_b128 v[70:73], v243
	ds_read_b128 v[86:89], v243 offset:512
	ds_read_b64_tr_b16 v[90:91], v241 offset:51200
	ds_read_b64_tr_b16 v[92:93], v241 offset:51712
	s_waitcnt lgkmcnt(8)
	v_mfma_f32_32x32x16_bf16 v[2:17], v[170:173], v[78:81], v[2:17]
	v_exp_f32_e32 v160, v160
	v_exp_f32_e32 v161, v161
	ds_read_b64_tr_b16 v[74:75], v241 offset:55296
	ds_read_b64_tr_b16 v[76:77], v241 offset:55808
	s_waitcnt lgkmcnt(8)
	v_mfma_f32_32x32x16_bf16 v[50:65], v[166:169], v[82:85], v[50:65]
	v_exp_f32_e32 v114, v114
	v_exp_f32_e32 v115, v115
	ds_read_b128 v[78:81], v243 offset:2048
	ds_read_b128 v[94:97], v243 offset:2560
	ds_read_b64_tr_b16 v[98:99], v241 offset:44032
	ds_read_b64_tr_b16 v[100:101], v241 offset:44544
	s_waitcnt lgkmcnt(10)
	v_mfma_f32_32x32x16_bf16 v[34:49], v[166:169], v[66:69], v[34:49]
	v_exp_f32_e32 v116, v116
	v_exp_f32_e32 v117, v117
	ds_read_b64_tr_b16 v[82:83], v241 offset:48128
	ds_read_b64_tr_b16 v[84:85], v241 offset:48640
	s_waitcnt lgkmcnt(8)
	v_mfma_f32_32x32x16_bf16 v[18:33], v[166:169], v[90:93], v[18:33]
	v_exp_f32_e32 v118, v118
	v_exp_f32_e32 v119, v119
	ds_read_b128 v[66:69], v243 offset:4096
	ds_read_b128 v[196:199], v243 offset:4608
	ds_read_b64_tr_b16 v[102:103], v241 offset:52224
	ds_read_b64_tr_b16 v[104:105], v241 offset:52736
	s_waitcnt lgkmcnt(10)
	v_mfma_f32_32x32x16_bf16 v[2:17], v[166:169], v[74:77], v[2:17]
	v_exp_f32_e32 v120, v120
	v_exp_f32_e32 v121, v121
	ds_read_b64_tr_b16 v[90:91], v241 offset:56320
	ds_read_b64_tr_b16 v[92:93], v241 offset:56832
	s_waitcnt lgkmcnt(8)
	v_mfma_f32_32x32x16_bf16 v[50:65], v[162:165], v[98:101], v[50:65]
	ds_read_b128 v[74:77], v243 offset:6144
	ds_read_b128 v[244:247], v243 offset:6656
	v_exp_f32_e32 v122, v122
	v_exp_f32_e32 v123, v123
	s_waitcnt lgkmcnt(8)
	v_mfma_f32_32x32x16_bf16 v[34:49], v[162:165], v[82:85], v[34:49]
	v_exp_f32_e32 v124, v124
	v_exp_f32_e32 v125, v125
	s_waitcnt lgkmcnt(4)
	v_mfma_f32_32x32x16_bf16 v[18:33], v[162:165], v[102:105], v[18:33]
	v_exp_f32_e32 v126, v126
	v_exp_f32_e32 v127, v127
	s_waitcnt lgkmcnt(2)
	v_mfma_f32_32x32x16_bf16 v[2:17], v[162:165], v[90:93], v[2:17]
	v_exp_f32_e32 v128, v128
	v_exp_f32_e32 v129, v129
	s_waitcnt vmcnt(2) lgkmcnt(0)
	s_barrier
	ds_read_b64_tr_b16 v[82:83], v241 offset:57344
	ds_read_b64_tr_b16 v[84:85], v241 offset:57856
	v_add_f32_e32 v90, v146, v147
	v_add_f32_e32 v90, v148, v90
	v_add_f32_e32 v90, v149, v90
	v_add_f32_e32 v90, v150, v90
	v_add_f32_e32 v90, v151, v90
	v_cvt_pk_bf16_f32 v174, v146, v147
	v_cvt_pk_bf16_f32 v175, v148, v149
	v_mfma_f32_32x32x16_bf16 v[130:145], v[70:73], v[190:193], 0
	ds_read_b64_tr_b16 v[70:71], v241 offset:61440
	ds_read_b64_tr_b16 v[72:73], v241 offset:61952
	v_mfma_f32_32x32x16_bf16 v[98:113], v[86:89], v[190:193], 0
	v_add_f32_e32 v90, v152, v90
	v_add_f32_e32 v90, v153, v90
	v_add_f32_e32 v90, v154, v90
	v_add_f32_e32 v90, v155, v90
	v_cvt_pk_bf16_f32 v176, v150, v151
	v_cvt_pk_bf16_f32 v177, v152, v153
	ds_read_b64_tr_b16 v[86:87], v242 offset:40960
	ds_read_b64_tr_b16 v[88:89], v242 offset:41472
	v_add_f32_e32 v90, v156, v90
	v_add_f32_e32 v90, v157, v90
	v_add_f32_e32 v90, v158, v90
	v_add_f32_e32 v90, v159, v90
	v_cvt_pk_bf16_f32 v170, v154, v155
	v_cvt_pk_bf16_f32 v171, v156, v157
	v_mfma_f32_32x32x16_bf16 v[130:145], v[78:81], v[186:189], v[130:145]
	ds_read_b64_tr_b16 v[78:79], v242 offset:45056
	ds_read_b64_tr_b16 v[80:81], v242 offset:45568
	v_mfma_f32_32x32x16_bf16 v[98:113], v[94:97], v[186:189], v[98:113]
	v_add_f32_e32 v90, v160, v90
	v_add_f32_e32 v90, v161, v90
	v_add_f32_e32 v90, v114, v90
	v_add_f32_e32 v90, v115, v90
	v_cvt_pk_bf16_f32 v172, v158, v159
	v_cvt_pk_bf16_f32 v173, v160, v161
	s_nop 0
	v_add_f32_e32 v90, v116, v90
	v_add_f32_e32 v90, v117, v90
	v_add_f32_e32 v90, v118, v90
	v_add_f32_e32 v90, v119, v90
	v_cvt_pk_bf16_f32 v166, v114, v115
	v_cvt_pk_bf16_f32 v167, v116, v117
	v_mfma_f32_32x32x16_bf16 v[130:145], v[66:69], v[182:185], v[130:145]
	v_mfma_f32_32x32x16_bf16 v[98:113], v[196:199], v[182:185], v[98:113]
	v_add_f32_e32 v66, v120, v90
	v_add_f32_e32 v66, v121, v66
	v_add_f32_e32 v66, v122, v66
	v_add_f32_e32 v66, v123, v66
	v_cvt_pk_bf16_f32 v168, v118, v119
	v_cvt_pk_bf16_f32 v169, v120, v121
	s_nop 0
	v_add_f32_e32 v66, v124, v66
	v_add_f32_e32 v66, v125, v66
	v_add_f32_e32 v66, v126, v66
	v_add_f32_e32 v66, v127, v66
	v_cvt_pk_bf16_f32 v162, v122, v123
	v_cvt_pk_bf16_f32 v163, v124, v125
	s_waitcnt lgkmcnt(9)
	v_mfma_f32_32x32x16_bf16 v[130:145], v[74:77], v[178:181], v[130:145]
	s_waitcnt lgkmcnt(8)
	v_mfma_f32_32x32x16_bf16 v[98:113], v[244:247], v[178:181], v[98:113]
	v_add_f32_e32 v66, v128, v66
	v_add_f32_e32 v66, v129, v66
	v_add_f32_e32 v114, 0, v66
	v_cvt_pk_bf16_f32 v164, v126, v127
	v_cvt_pk_bf16_f32 v165, v128, v129
	s_cmp_lg_u32 0, -1
	s_cselect_b32 s0, 0, 0
	s_add_i32 s0, s0, s90
	s_add_i32 s6, s0, 0xa000
	s_mov_b32 s7, m0
	s_mov_b32 m0, s6
	s_nop 0
	global_load_lds_dwordx4 v[218:219], off
	s_mov_b32 m0, s7
	s_add_i32 s0, s0, 0xc000
	s_mov_b32 s6, m0
	s_mov_b32 m0, s0
	s_nop 0
	global_load_lds_dwordx4 v[220:221], off
	s_mov_b32 m0, s6
	s_waitcnt lgkmcnt(6)
	v_mfma_f32_32x32x16_bf16 v[50:65], v[174:177], v[82:85], v[50:65]
	v_exp_f32_e32 v130, v130
	v_exp_f32_e32 v131, v131
	ds_read_b64_tr_b16 v[66:67], v241 offset:58368
	ds_read_b64_tr_b16 v[68:69], v241 offset:58880
	s_waitcnt lgkmcnt(6)
	v_mfma_f32_32x32x16_bf16 v[34:49], v[174:177], v[70:73], v[34:49]
	v_exp_f32_e32 v132, v132
	v_exp_f32_e32 v133, v133
	ds_read_b64_tr_b16 v[74:75], v241 offset:62464
	ds_read_b64_tr_b16 v[76:77], v241 offset:62976
	s_waitcnt lgkmcnt(6)
	v_mfma_f32_32x32x16_bf16 v[18:33], v[174:177], v[86:89], v[18:33]
	v_exp_f32_e32 v134, v134
	v_exp_f32_e32 v135, v135
	ds_read_b64_tr_b16 v[70:71], v242 offset:41984
	ds_read_b64_tr_b16 v[72:73], v242 offset:42496
	s_waitcnt lgkmcnt(6)
	v_mfma_f32_32x32x16_bf16 v[2:17], v[174:177], v[78:81], v[2:17]
	v_exp_f32_e32 v136, v136
	v_exp_f32_e32 v137, v137
	ds_read_b64_tr_b16 v[82:83], v242 offset:46080
	ds_read_b64_tr_b16 v[84:85], v242 offset:46592
	s_waitcnt lgkmcnt(6)
	v_mfma_f32_32x32x16_bf16 v[50:65], v[170:173], v[66:69], v[50:65]
	v_exp_f32_e32 v138, v138
	v_exp_f32_e32 v139, v139
	ds_read_b64_tr_b16 v[78:79], v241 offset:59392
	ds_read_b64_tr_b16 v[80:81], v241 offset:59904
	s_waitcnt lgkmcnt(6)
	v_mfma_f32_32x32x16_bf16 v[34:49], v[170:173], v[74:77], v[34:49]
	v_exp_f32_e32 v140, v140
	v_exp_f32_e32 v141, v141
	ds_read_b64_tr_b16 v[66:67], v241 offset:63488
	ds_read_b64_tr_b16 v[68:69], v241 offset:64000
	s_waitcnt lgkmcnt(6)
	v_mfma_f32_32x32x16_bf16 v[18:33], v[170:173], v[70:73], v[18:33]
	v_exp_f32_e32 v142, v142
	v_exp_f32_e32 v143, v143
	ds_read_b128 v[74:77], v243 offset:8192
	ds_read_b128 v[86:89], v243 offset:8704
	ds_read_b64_tr_b16 v[90:91], v242 offset:43008
	ds_read_b64_tr_b16 v[92:93], v242 offset:43520
	s_waitcnt lgkmcnt(8)
	v_mfma_f32_32x32x16_bf16 v[2:17], v[170:173], v[82:85], v[2:17]
	v_exp_f32_e32 v144, v144
	v_exp_f32_e32 v145, v145
	ds_read_b64_tr_b16 v[70:71], v242 offset:47104
	ds_read_b64_tr_b16 v[72:73], v242 offset:47616
	s_waitcnt lgkmcnt(8)
	v_mfma_f32_32x32x16_bf16 v[50:65], v[166:169], v[78:81], v[50:65]
	v_exp_f32_e32 v98, v98
	v_exp_f32_e32 v99, v99
	ds_read_b128 v[116:119], v243 offset:10240
	ds_read_b128 v[120:123], v243 offset:10752
	ds_read_b64_tr_b16 v[82:83], v241 offset:60416
	ds_read_b64_tr_b16 v[84:85], v241 offset:60928
	s_waitcnt lgkmcnt(10)
	v_mfma_f32_32x32x16_bf16 v[34:49], v[166:169], v[66:69], v[34:49]
	v_exp_f32_e32 v100, v100
	v_exp_f32_e32 v101, v101
	ds_read_b64_tr_b16 v[78:79], v241 offset:64512
	ds_read_b64_tr_b16 v[80:81], v241 offset:65024
	s_waitcnt lgkmcnt(8)
	v_mfma_f32_32x32x16_bf16 v[18:33], v[166:169], v[90:93], v[18:33]
	v_exp_f32_e32 v102, v102
	v_exp_f32_e32 v103, v103
	ds_read_b128 v[124:127], v243 offset:12288
	ds_read_b128 v[146:149], v243 offset:12800
	ds_read_b64_tr_b16 v[66:67], v242 offset:44032
	ds_read_b64_tr_b16 v[68:69], v242 offset:44544
	s_waitcnt lgkmcnt(10)
	v_mfma_f32_32x32x16_bf16 v[2:17], v[166:169], v[70:73], v[2:17]
	v_exp_f32_e32 v104, v104
	v_exp_f32_e32 v105, v105
	ds_read_b64_tr_b16 v[90:91], v242 offset:48128
	ds_read_b64_tr_b16 v[92:93], v242 offset:48640
	s_waitcnt lgkmcnt(8)
	v_mfma_f32_32x32x16_bf16 v[50:65], v[162:165], v[82:85], v[50:65]
	ds_read_b128 v[150:153], v243 offset:14336
	ds_read_b128 v[154:157], v243 offset:14848
	v_exp_f32_e32 v106, v106
	v_exp_f32_e32 v107, v107
	s_waitcnt lgkmcnt(8)
	v_mfma_f32_32x32x16_bf16 v[34:49], v[162:165], v[78:81], v[34:49]
	v_exp_f32_e32 v108, v108
	v_exp_f32_e32 v109, v109
	s_waitcnt lgkmcnt(4)
	v_mfma_f32_32x32x16_bf16 v[18:33], v[162:165], v[66:69], v[18:33]
	v_exp_f32_e32 v110, v110
	v_exp_f32_e32 v111, v111
	s_waitcnt lgkmcnt(2)
	v_mfma_f32_32x32x16_bf16 v[2:17], v[162:165], v[90:93], v[2:17]
	v_exp_f32_e32 v112, v112
	v_exp_f32_e32 v113, v113
	s_waitcnt vmcnt(0) lgkmcnt(0)
	s_barrier
; __device__ __forceinline__ void attn_unit(int b, int h, int qb, bool first, bool has_next, int nb, int nh, bf16_t* QO, const bf16_t* __restrict__ K, const bf16_t* __restrict__ V, float lam, char* shm) {
;     ...
;             const bf16_t* nk = (map == 0) ? ksrc + 1024 : K + (long)nb * SEQ * DM + (2 * nh) * 1024 + klane;
;             const bf16_t* nv = (map == 0) ? vsrc0 : V + (long)nb * SEQ * DM + nh * 2048 + vlane;
;             glds16(nk, (unsigned)__builtin_amdgcn_readfirstlane(kdst)); glds16(nv, (unsigned)__builtin_amdgcn_readfirstlane(vdst)); glds16(nv + 1024, (unsigned)__builtin_amdgcn_readfirstlane(vdst + 8192));
	ds_read_b64_tr_b16 v[158:159], v241 offset:24576
	ds_read_b64_tr_b16 v[160:161], v241 offset:25088
	v_add_f32_e32 v66, v130, v131
	v_add_f32_e32 v66, v132, v66
	v_add_f32_e32 v66, v133, v66
	v_add_f32_e32 v66, v134, v66
	v_add_f32_e32 v82, v135, v66
	v_mfma_f32_32x32x16_bf16 v[66:81], v[74:77], v[190:193], 0
	v_cvt_pk_bf16_f32 v174, v130, v131
	v_cvt_pk_bf16_f32 v175, v132, v133
	ds_read_b64_tr_b16 v[128:129], v241 offset:28672
	ds_read_b64_tr_b16 v[130:131], v241 offset:29184
	v_add_f32_e32 v82, v136, v82
	v_add_f32_e32 v82, v137, v82
	v_add_f32_e32 v82, v138, v82
	v_add_f32_e32 v115, v139, v82
	v_mfma_f32_32x32x16_bf16 v[82:97], v[86:89], v[190:193], 0
	v_cvt_pk_bf16_f32 v176, v134, v135
	v_cvt_pk_bf16_f32 v177, v136, v137
	ds_read_b64_tr_b16 v[132:133], v241 offset:32768
	ds_read_b64_tr_b16 v[134:135], v241 offset:33280
	v_mfma_f32_32x32x16_bf16 v[66:81], v[116:119], v[186:189], v[66:81]
	v_add_f32_e32 v115, v140, v115
	v_add_f32_e32 v115, v141, v115
	v_add_f32_e32 v115, v142, v115
	v_add_f32_e32 v115, v143, v115
	v_cvt_pk_bf16_f32 v170, v138, v139
	v_cvt_pk_bf16_f32 v171, v140, v141
	ds_read_b64_tr_b16 v[116:117], v241 offset:36864
	ds_read_b64_tr_b16 v[118:119], v241 offset:37376
	v_mfma_f32_32x32x16_bf16 v[82:97], v[120:123], v[186:189], v[82:97]
	v_add_f32_e32 v115, v144, v115
	v_add_f32_e32 v115, v145, v115
	v_add_f32_e32 v115, v98, v115
	v_add_f32_e32 v115, v99, v115
	v_cvt_pk_bf16_f32 v172, v142, v143
	v_cvt_pk_bf16_f32 v173, v144, v145
	v_mfma_f32_32x32x16_bf16 v[66:81], v[124:127], v[182:185], v[66:81]
	v_add_f32_e32 v115, v100, v115
	v_add_f32_e32 v115, v101, v115
	v_add_f32_e32 v115, v102, v115
	v_add_f32_e32 v115, v103, v115
	v_cvt_pk_bf16_f32 v166, v98, v99
	v_cvt_pk_bf16_f32 v167, v100, v101
	v_mfma_f32_32x32x16_bf16 v[82:97], v[146:149], v[182:185], v[82:97]
	v_add_f32_e32 v98, v104, v115
	v_add_f32_e32 v98, v105, v98
	v_add_f32_e32 v98, v106, v98
	v_add_f32_e32 v98, v107, v98
	v_cvt_pk_bf16_f32 v168, v102, v103
	v_cvt_pk_bf16_f32 v169, v104, v105
	s_waitcnt lgkmcnt(9)
	v_mfma_f32_32x32x16_bf16 v[66:81], v[150:153], v[178:181], v[66:81]
	v_add_f32_e32 v98, v108, v98
	v_add_f32_e32 v98, v109, v98
	v_add_f32_e32 v98, v110, v98
	v_add_f32_e32 v98, v111, v98
	v_cvt_pk_bf16_f32 v162, v106, v107
	v_cvt_pk_bf16_f32 v163, v108, v109
	s_waitcnt lgkmcnt(8)
	v_mfma_f32_32x32x16_bf16 v[82:97], v[154:157], v[178:181], v[82:97]
	v_add_f32_e32 v98, v112, v98
	v_add_f32_e32 v98, v113, v98
	v_add_f32_e32 v98, 0, v98
	v_cvt_pk_bf16_f32 v164, v110, v111
	v_cvt_pk_bf16_f32 v165, v112, v113
	s_waitcnt lgkmcnt(6)
	v_mfma_f32_32x32x16_bf16 v[50:65], v[174:177], v[158:161], v[50:65]
	v_exp_f32_e32 v66, v66
	v_exp_f32_e32 v67, v67
	s_or_b64 s[100:101], s[48:49], s[54:55]
	s_cmp_eq_u64 s[100:101], 0
	s_mov_b32 s101, 0
	s_cbranch_scc1 .Lqh_none
	v_lshl_add_u64 v[250:251], v[232:233], 0, s[2:3]
	s_mov_b32 s99, m0
	v_cndmask_b32_e64 v251, v223, v251, s[54:55]
	v_cndmask_b32_e64 v250, v222, v250, s[54:55]
	s_mov_b32 m0, s91
	s_nop 0
	global_load_lds_dwordx4 v[250:251], off
	s_mov_b32 m0, s99
	s_cmp_lg_u64 s[54:55], 0
	s_cbranch_scc1 .Lqh_same
	s_cmp_lg_u32 s15, 0x100
	s_cbranch_scc1 .Lqh_none
	s_lshl_b32 s100, s89, 1
	s_add_i32 s100, s100, 0x1000000
	s_branch .Lqh_ld
.Lqh_same:
	s_or_b32 s100, s89, 0x400
	s_lshl_b32 s100, s100, 1
.Lqh_ld:
	v_lshl_add_u64 v[252:253], v[226:227], 0, s[100:101]
	s_mov_b32 s101, 1
	global_load_dwordx4 v[190:193], v[252:253], off
	global_load_dwordx4 v[186:189], v[252:253], off offset:32
	global_load_dwordx4 v[182:185], v[252:253], off offset:1024
	global_load_dwordx4 v[178:181], v[252:253], off offset:1056
.Lqh_none:
	ds_read_b64_tr_b16 v[100:101], v241 offset:25600
	ds_read_b64_tr_b16 v[102:103], v241 offset:26112
	s_waitcnt lgkmcnt(6)
	v_mfma_f32_32x32x16_bf16 v[34:49], v[174:177], v[128:131], v[34:49]
	v_exp_f32_e32 v68, v68
	v_exp_f32_e32 v69, v69
	ds_read_b64_tr_b16 v[104:105], v241 offset:29696
	ds_read_b64_tr_b16 v[106:107], v241 offset:30208
	s_waitcnt lgkmcnt(6)
	v_mfma_f32_32x32x16_bf16 v[18:33], v[174:177], v[132:135], v[18:33]
	v_exp_f32_e32 v70, v70
	v_exp_f32_e32 v71, v71
	ds_read_b64_tr_b16 v[108:109], v241 offset:33792
	ds_read_b64_tr_b16 v[110:111], v241 offset:34304
	s_waitcnt lgkmcnt(6)
	v_mfma_f32_32x32x16_bf16 v[2:17], v[174:177], v[116:119], v[2:17]
	v_exp_f32_e32 v72, v72
	v_exp_f32_e32 v73, v73
	ds_read_b64_tr_b16 v[120:121], v241 offset:37888
	ds_read_b64_tr_b16 v[122:123], v241 offset:38400
	s_waitcnt lgkmcnt(6)
	v_mfma_f32_32x32x16_bf16 v[50:65], v[170:173], v[100:103], v[50:65]
	v_exp_f32_e32 v74, v74
	v_exp_f32_e32 v75, v75
	ds_read_b64_tr_b16 v[116:117], v241 offset:26624
	ds_read_b64_tr_b16 v[118:119], v241 offset:27136
	s_waitcnt lgkmcnt(6)
	v_mfma_f32_32x32x16_bf16 v[34:49], v[170:173], v[104:107], v[34:49]
	v_exp_f32_e32 v76, v76
	v_exp_f32_e32 v77, v77
	ds_read_b64_tr_b16 v[100:101], v241 offset:30720
	ds_read_b64_tr_b16 v[102:103], v241 offset:31232
	s_waitcnt lgkmcnt(6)
	v_mfma_f32_32x32x16_bf16 v[18:33], v[170:173], v[108:111], v[18:33]
	v_exp_f32_e32 v78, v78
	v_exp_f32_e32 v79, v79
	ds_read_b64_tr_b16 v[104:105], v241 offset:34816
	ds_read_b64_tr_b16 v[106:107], v241 offset:35328
	s_waitcnt lgkmcnt(6)
	v_mfma_f32_32x32x16_bf16 v[2:17], v[170:173], v[120:123], v[2:17]
	v_exp_f32_e32 v80, v80
	v_exp_f32_e32 v81, v81
	ds_read_b64_tr_b16 v[108:109], v241 offset:38912
	ds_read_b64_tr_b16 v[110:111], v241 offset:39424
	s_waitcnt lgkmcnt(6)
	v_mfma_f32_32x32x16_bf16 v[50:65], v[166:169], v[116:119], v[50:65]
	v_exp_f32_e32 v82, v82
	v_exp_f32_e32 v83, v83
	ds_read_b64_tr_b16 v[120:121], v241 offset:27648
	ds_read_b64_tr_b16 v[122:123], v241 offset:28160
	s_waitcnt lgkmcnt(6)
; __device__ __forceinline__ s16x4 vtr(lds_cptr p) { return __builtin_bit_cast(s16x4, __builtin_amdgcn_ds_read_tr16_b64_v4i16((LAS v4i16_t*)p)); }
; __device__ __forceinline__ void attn_unit(int b, int h, int qb, bool first, bool has_next, int nb, int nh, bf16_t* QO, const bf16_t* __restrict__ K, const bf16_t* __restrict__ V, float lam, char* shm) {
;     ...
;         { float sacc = pB0[0] + pB0[1];
; #pragma unroll
;           for (int r = 2; r < 16; ++r) sacc += pB0[r];
; #pragma unroll
;           for (int r = 0; r < 16; ++r) sacc += pB1[r];
;           l_reg += sacc;
;           pw0 = (u32x4){ATT_PK(pB0[0], pB0[1]), ATT_PK(pB0[2], pB0[3]), ATT_PK(pB0[4], pB0[5]), ATT_PK(pB0[6], pB0[7])};
;           pw1 = (u32x4){ATT_PK(pB0[8], pB0[9]), ATT_PK(pB0[10], pB0[11]), ATT_PK(pB0[12], pB0[13]), ATT_PK(pB0[14], pB0[15])};
;           pw2 = (u32x4){ATT_PK(pB1[0], pB1[1]), ATT_PK(pB1[2], pB1[3]), ATT_PK(pB1[4], pB1[5]), ATT_PK(pB1[6], pB1[7])};
;           pw3 = (u32x4){ATT_PK(pB1[8], pB1[9]), ATT_PK(pB1[10], pB1[11]), ATT_PK(pB1[12], pB1[13]), ATT_PK(pB1[14], pB1[15])};
;           ATT_SB();
;           const lds_cptr vp = vp0 + sl_cur * VSLOT;
; #pragma unroll
;           for (int d0 = 0; d0 < 4; ++d0) {
;               const s16x4 l0 = vtr(vp + d0 * 4096), h0 = vtr(vp + d0 * 4096 + 512), l1 = vtr(vp + d0 * 4096 + 1024), h1 = vtr(vp + d0 * 4096 + 1536);
;               const s16x4 l2 = vtr(vp + d0 * 4096 + 2048), h2 = vtr(vp + d0 * 4096 + 2560), l3 = vtr(vp + d0 * 4096 + 3072), h3 = vtr(vp + d0 * 4096 + 3584);
;               o[d0] = ATT_MFMA(PAF(0), ((bf16x8){l0[0], l0[1], l0[2], l0[3], h0[0], h0[1], h0[2], h0[3]}), o[d0]);
;               o[d0] = ATT_MFMA(PAF(1), ((bf16x8){l1[0], l1[1], l1[2], l1[3], h1[0], h1[1], h1[2], h1[3]}), o[d0]);
;               o[d0] = ATT_MFMA(PAF(2), ((bf16x8){l2[0], l2[1], l2[2], l2[3], h2[0], h2[1], h2[2], h2[3]}), o[d0]);
;               o[d0] = ATT_MFMA(PAF(3), ((bf16x8){l3[0], l3[1], l3[2], l3[3], h3[0], h3[1], h3[2], h3[3]}), o[d0]); } }
;     ...
;         ATT_SB();
;         asm volatile("s_waitcnt lgkmcnt(0)\n\ts_barrier" ::: "memory");
;         ATT_SB();
;         if (map == 0 || has_next) {
;             const bf16_t* nk = (map == 0) ? ksrc + 1024 : K + (long)nb * SEQ * DM + (2 * nh) * 1024 + klane;
;             const bf16_t* nv = (map == 0) ? vsrc0 : V + (long)nb * SEQ * DM + nh * 2048 + vlane;
	v_mfma_f32_32x32x16_bf16 v[34:49], v[166:169], v[100:103], v[34:49]
	v_exp_f32_e32 v84, v84
	v_exp_f32_e32 v85, v85
	ds_read_b64_tr_b16 v[116:117], v241 offset:31744
	ds_read_b64_tr_b16 v[118:119], v241 offset:32256
	s_waitcnt lgkmcnt(6)
	v_mfma_f32_32x32x16_bf16 v[18:33], v[166:169], v[104:107], v[18:33]
	v_exp_f32_e32 v86, v86
	v_exp_f32_e32 v87, v87
	ds_read_b64_tr_b16 v[100:101], v241 offset:35840
	ds_read_b64_tr_b16 v[102:103], v241 offset:36352
	s_waitcnt lgkmcnt(6)
	v_mfma_f32_32x32x16_bf16 v[2:17], v[166:169], v[108:111], v[2:17]
	v_exp_f32_e32 v88, v88
	v_exp_f32_e32 v89, v89
	ds_read_b64_tr_b16 v[104:105], v241 offset:39936
	ds_read_b64_tr_b16 v[106:107], v241 offset:40448
	s_waitcnt lgkmcnt(6)
	v_mfma_f32_32x32x16_bf16 v[50:65], v[162:165], v[120:123], v[50:65]
	v_exp_f32_e32 v90, v90
	v_exp_f32_e32 v91, v91
	s_waitcnt lgkmcnt(4)
	v_mfma_f32_32x32x16_bf16 v[34:49], v[162:165], v[116:119], v[34:49]
	v_exp_f32_e32 v92, v92
	v_exp_f32_e32 v93, v93
	s_waitcnt lgkmcnt(2)
	v_mfma_f32_32x32x16_bf16 v[18:33], v[162:165], v[100:103], v[18:33]
	v_exp_f32_e32 v94, v94
	v_exp_f32_e32 v95, v95
	s_waitcnt lgkmcnt(0)
	v_mfma_f32_32x32x16_bf16 v[2:17], v[162:165], v[104:107], v[2:17]
	v_exp_f32_e32 v96, v96
	v_exp_f32_e32 v97, v97
	v_cvt_pk_bf16_f32 v176, v70, v71
	v_cvt_pk_bf16_f32 v177, v72, v73
	v_cvt_pk_bf16_f32 v172, v78, v79
	v_cvt_pk_bf16_f32 v173, v80, v81
	v_cvt_pk_bf16_f32 v168, v86, v87
	v_cvt_pk_bf16_f32 v169, v88, v89
	v_cvt_pk_bf16_f32 v164, v94, v95
	v_cvt_pk_bf16_f32 v165, v96, v97
	v_cvt_pk_bf16_f32 v174, v66, v67
	v_cvt_pk_bf16_f32 v175, v68, v69
	v_cvt_pk_bf16_f32 v170, v74, v75
	v_cvt_pk_bf16_f32 v171, v76, v77
	v_cvt_pk_bf16_f32 v166, v82, v83
	v_cvt_pk_bf16_f32 v167, v84, v85
	v_cvt_pk_bf16_f32 v162, v90, v91
	v_cvt_pk_bf16_f32 v163, v92, v93
	ds_read_b64_tr_b16 v[100:101], v241 offset:40960
	ds_read_b64_tr_b16 v[102:103], v241 offset:41472
	ds_read_b64_tr_b16 v[104:105], v241 offset:41984
	ds_read_b64_tr_b16 v[106:107], v241 offset:42496
	s_waitcnt lgkmcnt(2)
	v_mfma_f32_32x32x16_bf16 v[50:65], v[174:177], v[100:103], v[50:65]
	s_waitcnt lgkmcnt(0)
	v_mfma_f32_32x32x16_bf16 v[50:65], v[170:173], v[104:107], v[50:65]
	ds_read_b64_tr_b16 v[100:101], v241 offset:43008
	ds_read_b64_tr_b16 v[102:103], v241 offset:43520
	ds_read_b64_tr_b16 v[104:105], v241 offset:44032
	ds_read_b64_tr_b16 v[106:107], v241 offset:44544
	s_waitcnt lgkmcnt(2)
	v_mfma_f32_32x32x16_bf16 v[50:65], v[166:169], v[100:103], v[50:65]
	s_waitcnt lgkmcnt(0)
	v_mfma_f32_32x32x16_bf16 v[50:65], v[162:165], v[104:107], v[50:65]
	ds_read_b64_tr_b16 v[100:101], v241 offset:45056
	ds_read_b64_tr_b16 v[102:103], v241 offset:45568
	ds_read_b64_tr_b16 v[104:105], v241 offset:46080
	ds_read_b64_tr_b16 v[106:107], v241 offset:46592
	s_waitcnt lgkmcnt(2)
	v_mfma_f32_32x32x16_bf16 v[34:49], v[174:177], v[100:103], v[34:49]
	s_waitcnt lgkmcnt(0)
	v_mfma_f32_32x32x16_bf16 v[34:49], v[170:173], v[104:107], v[34:49]
	ds_read_b64_tr_b16 v[100:101], v241 offset:47104
	ds_read_b64_tr_b16 v[102:103], v241 offset:47616
	ds_read_b64_tr_b16 v[104:105], v241 offset:48128
	ds_read_b64_tr_b16 v[106:107], v241 offset:48640
	s_waitcnt lgkmcnt(2)
	v_mfma_f32_32x32x16_bf16 v[34:49], v[166:169], v[100:103], v[34:49]
	s_waitcnt lgkmcnt(0)
	v_mfma_f32_32x32x16_bf16 v[34:49], v[162:165], v[104:107], v[34:49]
	ds_read_b64_tr_b16 v[100:101], v241 offset:49152
	ds_read_b64_tr_b16 v[102:103], v241 offset:49664
	ds_read_b64_tr_b16 v[104:105], v241 offset:50176
	ds_read_b64_tr_b16 v[106:107], v241 offset:50688
	s_waitcnt lgkmcnt(2)
	v_mfma_f32_32x32x16_bf16 v[18:33], v[174:177], v[100:103], v[18:33]
	s_waitcnt lgkmcnt(0)
	v_mfma_f32_32x32x16_bf16 v[18:33], v[170:173], v[104:107], v[18:33]
	ds_read_b64_tr_b16 v[100:101], v241 offset:51200
	ds_read_b64_tr_b16 v[102:103], v241 offset:51712
	ds_read_b64_tr_b16 v[104:105], v241 offset:52224
	ds_read_b64_tr_b16 v[106:107], v241 offset:52736
	s_waitcnt lgkmcnt(2)
	v_mfma_f32_32x32x16_bf16 v[18:33], v[166:169], v[100:103], v[18:33]
	s_waitcnt lgkmcnt(0)
	v_mfma_f32_32x32x16_bf16 v[18:33], v[162:165], v[104:107], v[18:33]
	ds_read_b64_tr_b16 v[100:101], v241 offset:53248
	ds_read_b64_tr_b16 v[102:103], v241 offset:53760
	ds_read_b64_tr_b16 v[104:105], v241 offset:54272
	ds_read_b64_tr_b16 v[106:107], v241 offset:54784
	s_waitcnt lgkmcnt(2)
	v_mfma_f32_32x32x16_bf16 v[2:17], v[174:177], v[100:103], v[2:17]
	s_waitcnt lgkmcnt(0)
	v_mfma_f32_32x32x16_bf16 v[2:17], v[170:173], v[104:107], v[2:17]
	ds_read_b64_tr_b16 v[100:101], v241 offset:55296
	ds_read_b64_tr_b16 v[102:103], v241 offset:55808
	ds_read_b64_tr_b16 v[104:105], v241 offset:56320
	ds_read_b64_tr_b16 v[106:107], v241 offset:56832
	s_waitcnt lgkmcnt(2)
	v_mfma_f32_32x32x16_bf16 v[2:17], v[166:169], v[100:103], v[2:17]
	s_waitcnt lgkmcnt(0)
	v_mfma_f32_32x32x16_bf16 v[2:17], v[162:165], v[104:107], v[2:17]
	s_waitcnt lgkmcnt(0)
	s_barrier
	s_or_b64 s[6:7], s[48:49], s[54:55]
	s_andn2_b64 vcc, exec, s[6:7]
	s_cbranch_vccnz .LBB0_378
	v_lshl_add_u64 v[100:101], v[232:233], 0, s[2:3]
	v_cndmask_b32_e64 v101, v223, v101, s[54:55]
	v_cndmask_b32_e64 v100, v222, v100, s[54:55]
	v_cndmask_b32_e64 v103, v225, v205, s[54:55]
	v_cndmask_b32_e64 v102, v224, v204, s[54:55]
	s_mov_b32 s0, m0
	s_mov_b32 m0, s92
	s_nop 0
	global_load_lds_dwordx4 v[102:103], off
	s_mov_b32 m0, s0
	s_cmp_lg_u32 0, -1
	s_cselect_b32 s0, 0, 0
	s_add_i32 s0, s0, s90
	v_lshl_add_u64 v[102:103], v[102:103], 0, s[2:3]
	s_add_i32 s6, s0, 0x8000
	s_mov_b32 s7, m0
	s_mov_b32 m0, s6
	s_nop 0
	global_load_lds_dwordx4 v[102:103], off
	s_mov_b32 m0, s7
	v_lshl_add_u64 v[102:103], v[100:101], 0, s[4:5]
	s_add_i32 s6, s0, 0x2000
	s_mov_b32 s7, m0
	s_mov_b32 m0, s6
	s_nop 0
	global_load_lds_dwordx4 v[102:103], off
	s_mov_b32 m0, s7
	v_lshl_add_u64 v[100:101], v[100:101], 0, s[22:23]
	s_addk_i32 s0, 0x4000
	s_mov_b32 s6, m0
	s_mov_b32 m0, s0
	s_nop 0
	global_load_lds_dwordx4 v[100:101], off
	s_mov_b32 m0, s6

; __global__ void __launch_bounds__(512, 2) fwd_kernel(Args args) {
	.amdhsa_kernel _Z10fwd_kernel4Args
		.amdhsa_group_segment_fixed_size 0
		.amdhsa_private_segment_fixed_size 0
		.amdhsa_kernarg_size 432
		.amdhsa_user_sgpr_count 2
		.amdhsa_user_sgpr_dispatch_ptr 0
		.amdhsa_user_sgpr_queue_ptr 0
		.amdhsa_user_sgpr_kernarg_segment_ptr 1
		.amdhsa_user_sgpr_dispatch_id 0
		.amdhsa_user_sgpr_kernarg_preload_length 0
		.amdhsa_user_sgpr_kernarg_preload_offset 0
		.amdhsa_user_sgpr_private_segment_size 0
		.amdhsa_uses_dynamic_stack 0
		.amdhsa_enable_private_segment 0
		.amdhsa_system_sgpr_workgroup_id_x 1
		.amdhsa_system_sgpr_workgroup_id_y 0
		.amdhsa_system_sgpr_workgroup_id_z 0
		.amdhsa_system_sgpr_workgroup_info 0
		.amdhsa_system_vgpr_workitem_id 0
		.amdhsa_next_free_vgpr 254
		.amdhsa_next_free_sgpr 102
		.amdhsa_accum_offset 256
		.amdhsa_reserve_vcc 1
		.amdhsa_float_round_mode_32 0
		.amdhsa_float_round_mode_16_64 0
		.amdhsa_float_denorm_mode_32 3
		.amdhsa_float_denorm_mode_16_64 3
		.amdhsa_dx10_clamp 1
		.amdhsa_ieee_mode 1
		.amdhsa_fp16_overflow 0
		.amdhsa_tg_split 0
		.amdhsa_exception_fp_ieee_invalid_op 0
		.amdhsa_exception_fp_denorm_src 0
		.amdhsa_exception_fp_ieee_div_zero 0
		.amdhsa_exception_fp_ieee_overflow 0
		.amdhsa_exception_fp_ieee_underflow 0
		.amdhsa_exception_fp_ieee_inexact 0
		.amdhsa_exception_int_div_zero 0
	.end_amdhsa_kernel

; __global__ void __launch_bounds__(512, 2) fwd_kernel(Args args) {
amdhsa.kernels:
  - .agpr_count:     0
    .args:
      - .offset:         0
        .size:           176
        .value_kind:     by_value
      - .offset:         176
        .size:           4
        .value_kind:     hidden_block_count_x
      - .offset:         180
        .size:           4
        .value_kind:     hidden_block_count_y
      - .offset:         184
        .size:           4
        .value_kind:     hidden_block_count_z
      - .offset:         188
        .size:           2
        .value_kind:     hidden_group_size_x
      - .offset:         190
        .size:           2
        .value_kind:     hidden_group_size_y
      - .offset:         192
        .size:           2
        .value_kind:     hidden_group_size_z
      - .offset:         194
        .size:           2
        .value_kind:     hidden_remainder_x
      - .offset:         196
        .size:           2
        .value_kind:     hidden_remainder_y
      - .offset:         198
        .size:           2
        .value_kind:     hidden_remainder_z
      - .offset:         216
        .size:           8
        .value_kind:     hidden_global_offset_x
      - .offset:         224
        .size:           8
        .value_kind:     hidden_global_offset_y
      - .offset:         232
        .size:           8
        .value_kind:     hidden_global_offset_z
      - .offset:         240
        .size:           2
        .value_kind:     hidden_grid_dims
      - .offset:         296
        .size:           4
        .value_kind:     hidden_dynamic_lds_size
    .group_segment_fixed_size: 0
    .kernarg_segment_align: 8
    .kernarg_segment_size: 432
    .language:       OpenCL C
    .language_version:
      - 2
      - 0
    .max_flat_workgroup_size: 512
    .name:           _Z10fwd_kernel4Args
    .private_segment_fixed_size: 0
    .sgpr_count:     108
    .sgpr_spill_count: 22
    .symbol:         _Z10fwd_kernel4Args.kd
    .uniform_work_group_size: 1
    .uses_dynamic_stack: false
    .vgpr_count:     254
    .vgpr_spill_count: 0
    .wavefront_size: 64
